# attention loop: one static s_setprio 1 for waves 4-7 (younger half), reset after the loop
# baseline (speedup 1.0000x reference)
.LBB0_428:
	s_ashr_i32 s0, s18, 6
	s_add_i32 s4, s0, s19
	s_ashr_i32 s16, s4, 2
	v_mov_b32_e32 v132, v188
	s_ashr_i32 s17, s16, 31
	v_readfirstlane_b32 s34, v132
	s_lshl_b32 s5, s18, 7
	s_bfe_u32 s31, s34, 0x20006
	s_lshl_b64 s[2:3], s[16:17], 13
	s_and_b32 s0, s5, 0x1f80
	s_or_b32 s0, s2, s0
	s_lshl_b32 s2, s31, 5
	v_and_b32_e32 v202, 31, v132
	s_or_b32 s0, s0, s2
	v_or_b32_e32 v176, s0, v202
	v_mad_u64_u32 v[16:17], s[0:1], v176, s20, v[172:173]
	s_lshl_b32 s0, s4, 7
	s_ashr_i32 s30, s34, 8
	s_and_b32 s0, s0, 0x180
	v_mad_i32_i24 v17, s3, v189, v17
	s_lshl_b32 s12, s0, 1
	s_lshl_b32 s0, s30, 6
	v_bfe_u32 v133, v132, 5, 1
	v_lshl_add_u64 v[16:17], v[16:17], 0, s[12:13]
	s_ashr_i32 s1, s0, 31
	v_lshl_add_u64 v[16:17], s[0:1], 1, v[16:17]
	v_lshlrev_b32_e32 v166, 4, v133
	v_lshl_add_u64 v[16:17], v[16:17], 0, v[166:167]
	global_load_dwordx4 v[90:93], v[16:17], off offset:3136
	global_load_dwordx4 v[96:99], v[16:17], off offset:3168
	global_load_dwordx4 v[108:111], v[16:17], off offset:3072
	global_load_dwordx4 v[112:115], v[16:17], off offset:3104
	v_cmp_lt_i32_e32 vcc, v191, v192
	s_or_b32 s0, s2, s5
	s_lshl_b32 s0, s0, 1
	v_cndmask_b32_e32 v16, v190, v191, vcc
	v_lshlrev_b32_e32 v195, 2, v16
	v_and_b32_e32 v16, 32, v132
	global_load_dwordx4 v[40:43], v16, s[62:63] offset:144
	global_load_dwordx4 v[44:47], v16, s[62:63] offset:128
	global_load_dwordx4 v[28:31], v16, s[62:63] offset:208
	global_load_dwordx4 v[36:39], v16, s[62:63] offset:192
	global_load_dwordx4 v[72:75], v16, s[62:63] offset:16
	global_load_dwordx4 v[76:79], v16, s[62:63]
	global_load_dwordx4 v[64:67], v16, s[62:63] offset:80
	global_load_dwordx4 v[68:71], v16, s[62:63] offset:64
	v_lshlrev_b32_e32 v48, 6, v133
	v_and_or_b32 v16, s2, 32, v202
	s_and_b32 s0, s0, 0x3f80
	v_lshl_or_b32 v32, v16, 7, v48
	v_or_b32_e32 v60, s0, v48
	global_load_dwordx4 v[16:19], v32, s[10:11] offset:48
	global_load_dwordx4 v[20:23], v32, s[10:11] offset:32
	global_load_dwordx4 v[24:27], v32, s[10:11] offset:16
	s_nop 0
	global_load_dwordx4 v[32:35], v32, s[10:11]
	s_nop 0
	global_load_dwordx4 v[48:51], v60, s[10:11] offset:48
	global_load_dwordx4 v[52:55], v60, s[10:11] offset:32
	global_load_dwordx4 v[56:59], v60, s[10:11] offset:16
	s_nop 0
	global_load_dwordx4 v[60:63], v60, s[10:11]
	v_mov_b32_e32 v177, s3
	v_cmp_gt_i32_e32 vcc, s21, v132
	s_waitcnt vmcnt(19)
	v_lshlrev_b32_e32 v84, 16, v93
	s_waitcnt vmcnt(18)
	v_lshlrev_b32_e32 v80, 16, v99
	v_and_b32_e32 v81, 0xffff0000, v99
	v_lshlrev_b32_e32 v82, 16, v98
	v_and_b32_e32 v83, 0xffff0000, v98
	s_waitcnt vmcnt(17)
	v_lshlrev_b32_e32 v98, 16, v111
	v_and_b32_e32 v99, 0xffff0000, v111
	v_lshlrev_b32_e32 v102, 16, v110
	v_and_b32_e32 v103, 0xffff0000, v110
	v_lshlrev_b32_e32 v110, 16, v108
	v_and_b32_e32 v111, 0xffff0000, v108
	v_lshlrev_b32_e32 v106, 16, v109
	v_and_b32_e32 v107, 0xffff0000, v109
	v_pk_mul_f32 v[148:149], v[110:111], v[110:111]
	v_pk_mul_f32 v[144:145], v[106:107], v[106:107]
	v_add_f32_e32 v148, v148, v149
	v_add_f32_e32 v144, v144, v148
	v_pk_mul_f32 v[142:143], v[102:103], v[102:103]
	v_add_f32_e32 v144, v145, v144
	v_add_f32_e32 v142, v142, v144
	v_pk_mul_f32 v[138:139], v[98:99], v[98:99]
	v_add_f32_e32 v142, v143, v142
	s_waitcnt vmcnt(16)
	v_lshlrev_b32_e32 v108, 16, v112
	v_and_b32_e32 v109, 0xffff0000, v112
	v_add_f32_e32 v138, v138, v142
	v_lshlrev_b32_e32 v104, 16, v113
	v_and_b32_e32 v105, 0xffff0000, v113
	v_pk_mul_f32 v[112:113], v[108:109], v[108:109]
	v_add_f32_e32 v138, v139, v138
	v_add_f32_e32 v112, v112, v138
	v_pk_mul_f32 v[146:147], v[104:105], v[104:105]
	v_add_f32_e32 v112, v113, v112
	v_lshlrev_b32_e32 v100, 16, v114
	v_and_b32_e32 v101, 0xffff0000, v114
	v_add_f32_e32 v112, v146, v112
	v_and_b32_e32 v85, 0xffff0000, v93
	v_lshlrev_b32_e32 v88, 16, v92
	v_and_b32_e32 v89, 0xffff0000, v92
	v_lshlrev_b32_e32 v92, 16, v91
	v_and_b32_e32 v93, 0xffff0000, v91
	v_lshlrev_b32_e32 v86, 16, v97
	v_and_b32_e32 v87, 0xffff0000, v97
	v_lshlrev_b32_e32 v94, 16, v90
	v_and_b32_e32 v95, 0xffff0000, v90
	v_lshlrev_b32_e32 v90, 16, v96
	v_and_b32_e32 v91, 0xffff0000, v96
	v_lshlrev_b32_e32 v96, 16, v115
	v_and_b32_e32 v97, 0xffff0000, v115
	v_pk_mul_f32 v[114:115], v[100:101], v[100:101]
	v_add_f32_e32 v112, v147, v112
	v_add_f32_e32 v112, v114, v112
	v_pk_mul_f32 v[140:141], v[96:97], v[96:97]
	v_add_f32_e32 v112, v115, v112
	v_add_f32_e32 v112, v140, v112
	v_pk_mul_f32 v[134:135], v[94:95], v[94:95]
	v_add_f32_e32 v112, v141, v112
	v_add_f32_e32 v112, v134, v112
	v_pk_mul_f32 v[124:125], v[92:93], v[92:93]
	v_add_f32_e32 v112, v135, v112
	v_add_f32_e32 v112, v124, v112
	v_pk_mul_f32 v[120:121], v[88:89], v[88:89]
	v_add_f32_e32 v112, v125, v112
	v_add_f32_e32 v112, v120, v112
	v_pk_mul_f32 v[116:117], v[84:85], v[84:85]
	v_add_f32_e32 v112, v121, v112
	v_add_f32_e32 v112, v116, v112
	v_pk_mul_f32 v[136:137], v[90:91], v[90:91]
	v_add_f32_e32 v112, v117, v112
	v_add_f32_e32 v112, v136, v112
	v_pk_mul_f32 v[126:127], v[86:87], v[86:87]
	v_add_f32_e32 v112, v137, v112
	v_add_f32_e32 v112, v126, v112
	v_pk_mul_f32 v[122:123], v[82:83], v[82:83]
	v_add_f32_e32 v112, v127, v112
	v_add_f32_e32 v112, v122, v112
	v_pk_mul_f32 v[118:119], v[80:81], v[80:81]
	v_add_f32_e32 v112, v123, v112
	v_add_f32_e32 v112, v118, v112
	v_add_f32_e32 v134, v119, v112
	ds_bpermute_b32 v135, v195, v134
	v_lshrrev_b32_e32 v112, 6, v188
	v_lshrrev_b32_e32 v113, 4, v190
	v_and_b32_e32 v114, 15, v190
	v_lshl_add_u32 v115, v112, 3, v113
	v_and_b32_e32 v116, 15, v115
	v_xor_b32_e32 v116, v114, v116
	v_mul_u32_u24_e32 v117, 0x1a00, v115
	v_lshl_add_u32 v181, v116, 4, v117
	v_add_u32_e32 v118, 4, v115
	v_and_b32_e32 v116, 15, v118
	v_xor_b32_e32 v116, v114, v116
	v_mul_u32_u24_e32 v118, 0x1a00, v118
	v_lshl_add_u32 v165, v116, 4, v118
	v_lshlrev_b32_e32 v116, 2, v113
	v_xor_b32_e32 v116, v114, v116
	v_lshl_add_u32 v116, v116, 4, v117
	v_add_u32_e32 v207, 0x400, v116
	v_add_u32_e32 v208, 0x6c00, v116
	s_lshl_b32 s1, s16, 8
	s_add_i32 s1, s1, 0x8000
	s_mul_i32 s2, s1, 0x1a00
	s_add_u32 s22, s8, s12
	s_addc_u32 s23, s9, 0
	s_add_u32 s22, s22, 0x1000
	s_addc_u32 s23, s23, 0
	s_add_u32 s36, s22, s2
	s_addc_u32 s37, s23, 0
	s_lshl_b32 s3, s16, 13
	s_mul_i32 s3, s3, 0x1a00
	s_add_u32 s38, s22, s3
	s_addc_u32 s39, s23, 0
	s_lshr_b32 s17, s34, 6
	s_lshl_b32 s17, s17, 11
	s_add_i32 m0, s17, 0
	s_nop 0
	global_load_lds_dwordx4 v181, s[36:37]
	s_add_i32 m0, s17, 1024
	s_nop 0
	global_load_lds_dwordx4 v165, s[36:37]
	s_add_i32 m0, s17, 16384
	s_nop 0
	global_load_lds_dwordx4 v207, s[36:37]
	s_add_i32 m0, s17, 17408
	s_nop 0
	global_load_lds_dwordx4 v208, s[36:37]
	s_add_u32 s36, s36, 0x68000
	s_addc_u32 s37, s37, 0
	s_add_i32 m0, s17, 32768
	s_nop 0
	global_load_lds_dwordx4 v181, s[36:37]
	s_add_i32 m0, s17, 33792
	s_nop 0
	global_load_lds_dwordx4 v165, s[36:37]
	s_add_i32 m0, s17, 49152
	s_nop 0
	global_load_lds_dwordx4 v207, s[36:37]
	s_add_i32 m0, s17, 50176
	s_nop 0
	global_load_lds_dwordx4 v208, s[36:37]
	s_add_u32 s36, s36, 0x68000
	s_addc_u32 s37, s37, 0
	s_add_i32 m0, s17, 65536
	s_nop 0
	global_load_lds_dwordx4 v181, s[36:37]
	s_add_i32 m0, s17, 66560
	s_nop 0
	global_load_lds_dwordx4 v165, s[36:37]
	s_add_i32 m0, s17, 81920
	s_nop 0
	global_load_lds_dwordx4 v207, s[36:37]
	s_add_i32 m0, s17, 82944
	s_nop 0
	global_load_lds_dwordx4 v208, s[36:37]
	s_add_u32 s36, s36, 0x68000
	s_addc_u32 s37, s37, 0
	v_and_b32_e32 v112, 31, v190
	v_lshrrev_b32_e32 v113, 5, v190
	v_lshrrev_b32_e32 v114, 8, v188
	v_lshl_or_b32 v113, v114, 3, v113
	v_and_b32_e32 v115, 15, v112
	v_xor_b32_e32 v113, v113, v115
	v_lshlrev_b32_e32 v112, 8, v112
	v_lshl_add_u32 v178, v113, 4, v112
	v_xor_b32_e32 v116, 2, v113
	v_lshl_add_u32 v128, v116, 4, v112
	v_xor_b32_e32 v116, 4, v113
	v_lshl_add_u32 v130, v116, 4, v112
	v_xor_b32_e32 v116, 6, v113
	v_lshl_add_u32 v131, v116, 4, v112
	v_add_u32_e32 v180, 0x10000, v178
	v_add_u32_e32 v189, 0x10000, v128
	v_add_u32_e32 v191, 0x10000, v130
	v_add_u32_e32 v192, 0x10000, v131
	v_and_b32_e32 v112, 3, v190
	v_bfe_u32 v113, v190, 2, 2
	v_bfe_u32 v114, v190, 4, 1
	v_lshrrev_b32_e32 v115, 5, v190
	v_lshlrev_b32_e32 v115, 10, v115
	v_lshl_add_u32 v115, v113, 8, v115
	v_lshl_add_u32 v115, v114, 5, v115
	v_lshl_add_u32 v115, v112, 3, v115
	v_add_u32_e32 v115, 0x4000, v115
	v_lshl_add_u32 v184, v113, 6, v115
	v_xor_b32_e32 v116, 1, v113
	v_lshl_add_u32 v185, v116, 6, v115
	v_xor_b32_e32 v116, 2, v113
	v_lshl_add_u32 v186, v116, 6, v115
	v_xor_b32_e32 v116, 3, v113
	v_lshl_add_u32 v187, v116, 6, v115
	v_add_u32_e32 v198, 0x10000, v184
	v_add_u32_e32 v199, 0x10000, v185
	v_add_u32_e32 v201, 0x10000, v186
	v_add_u32_e32 v203, 0x10000, v187
	v_mov_b32_e32 v148, 0
	v_mov_b32_e32 v149, 0
	v_mov_b32_e32 v150, 0
	v_mov_b32_e32 v151, 0
	v_lshlrev_b32_e32 v112, 4, v188
	v_add_u32_e32 v112, 0x1e000, v112
	ds_write_b128 v112, v[148:151]
	s_waitcnt vmcnt(12)
	s_waitcnt lgkmcnt(0)
	v_lshrrev_b32_e32 v136, 2, v132
	v_lshlrev_b32_e32 v179, 2, v133
	v_and_or_b32 v133, v136, 3, v179
	v_mul_u32_u24_e32 v204, 0x140, v133
	v_lshlrev_b32_e32 v133, 1, v132
	v_and_b32_e32 v205, 32, v133
	v_add_f32_e32 v133, v134, v135
	v_fmamk_f32 v133, v133, 0x3c800000, v193
	v_mul_f32_e32 v134, 0x4b800000, v133
	v_cmp_gt_f32_e32 vcc, s27, v133
	v_lshlrev_b32_e32 v132, 3, v132
	v_and_b32_e32 v206, 24, v132
	v_cndmask_b32_e32 v133, v133, v134, vcc
	v_rsq_f32_e32 v133, v133
	v_add3_u32 v197, v204, v205, v206
	v_add_u32_e32 v200, 0, v197
	s_lshl_b32 s0, s30, 7
	v_mul_f32_e32 v132, 0x45800000, v133
	v_cndmask_b32_e32 v132, v133, v132, vcc
	v_mul_f32_e32 v132, 0x3e38aa3b, v132
	v_pk_mul_f32 v[68:69], v[68:69], v[132:133] op_sel_hi:[1,0]
	v_pk_mul_f32 v[30:31], v[30:31], v[132:133] op_sel_hi:[1,0]
	v_pk_mul_f32 v[76:77], v[76:77], v[132:133] op_sel_hi:[1,0]
	v_pk_mul_f32 v[68:69], v[68:69], v[108:109]
	v_pk_mul_f32 v[30:31], v[30:31], v[80:81]
	v_mov_b32_e32 v80, v60
	v_mov_b32_e32 v81, v62
	v_mov_b32_e32 v62, v61
	v_pk_mul_f32 v[76:77], v[76:77], v[110:111]
	v_pk_mul_f32 v[70:71], v[70:71], v[132:133] op_sel_hi:[1,0]
	v_pk_mul_f32 v[60:61], v[62:63], v[68:69]
	v_pk_mul_f32 v[68:69], v[80:81], v[68:69]
	v_pk_mul_f32 v[78:79], v[78:79], v[132:133] op_sel_hi:[1,0]
	v_pk_mul_f32 v[70:71], v[70:71], v[104:105]
	v_pk_fma_f32 v[62:63], v[62:63], v[76:77], v[68:69]
	v_mov_b32_e32 v69, v58
	v_mov_b32_e32 v58, v57
	v_pk_mul_f32 v[78:79], v[78:79], v[106:107]
	v_mov_b32_e32 v68, v56
	v_pk_mul_f32 v[56:57], v[58:59], v[70:71]
	v_pk_mul_f32 v[64:65], v[64:65], v[132:133] op_sel_hi:[1,0]
	v_pk_fma_f32 v[56:57], v[68:69], v[78:79], v[56:57] neg_lo:[0,0,1] neg_hi:[0,0,1]
	v_pk_mul_f32 v[68:69], v[68:69], v[70:71]
	v_pk_mul_f32 v[72:73], v[72:73], v[132:133] op_sel_hi:[1,0]
	v_pk_mul_f32 v[64:65], v[64:65], v[100:101]
	v_pk_fma_f32 v[58:59], v[58:59], v[78:79], v[68:69]
	v_mov_b32_e32 v68, v52
	v_mov_b32_e32 v69, v54
	v_mov_b32_e32 v54, v53
	v_pk_mul_f32 v[72:73], v[72:73], v[102:103]
	v_pk_mul_f32 v[66:67], v[66:67], v[132:133] op_sel_hi:[1,0]
	v_pk_mul_f32 v[52:53], v[54:55], v[64:65]
	v_pk_mul_f32 v[64:65], v[68:69], v[64:65]
	v_pk_mul_f32 v[74:75], v[74:75], v[132:133] op_sel_hi:[1,0]
	v_pk_mul_f32 v[66:67], v[66:67], v[96:97]
	v_pk_fma_f32 v[54:55], v[54:55], v[72:73], v[64:65]
	v_mov_b32_e32 v65, v50
	v_mov_b32_e32 v50, v49
	v_pk_mul_f32 v[74:75], v[74:75], v[98:99]
	v_mov_b32_e32 v64, v48
	v_pk_mul_f32 v[48:49], v[50:51], v[66:67]
	v_pk_mul_f32 v[36:37], v[36:37], v[132:133] op_sel_hi:[1,0]
	v_pk_fma_f32 v[48:49], v[74:75], v[64:65], v[48:49] neg_lo:[0,0,1] neg_hi:[0,0,1]
	v_pk_mul_f32 v[64:65], v[64:65], v[66:67]
	v_pk_mul_f32 v[44:45], v[44:45], v[132:133] op_sel_hi:[1,0]
	v_pk_mul_f32 v[36:37], v[36:37], v[90:91]
	v_pk_fma_f32 v[50:51], v[50:51], v[74:75], v[64:65]
	v_mov_b32_e32 v64, v32
	v_mov_b32_e32 v65, v34
	v_mov_b32_e32 v34, v33
	v_pk_mul_f32 v[44:45], v[44:45], v[94:95]
	v_pk_mul_f32 v[38:39], v[38:39], v[132:133] op_sel_hi:[1,0]
	v_pk_mul_f32 v[32:33], v[36:37], v[34:35]
	v_pk_mul_f32 v[36:37], v[36:37], v[64:65]
	v_pk_mul_f32 v[46:47], v[46:47], v[132:133] op_sel_hi:[1,0]
	v_pk_mul_f32 v[38:39], v[38:39], v[86:87]
	v_pk_fma_f32 v[34:35], v[44:45], v[34:35], v[36:37]
	v_mov_b32_e32 v37, v26
	v_mov_b32_e32 v26, v25
	v_pk_mul_f32 v[46:47], v[46:47], v[92:93]
	v_mov_b32_e32 v36, v24
	v_pk_mul_f32 v[24:25], v[38:39], v[26:27]
	v_pk_mul_f32 v[28:29], v[28:29], v[132:133] op_sel_hi:[1,0]
	v_pk_fma_f32 v[24:25], v[46:47], v[36:37], v[24:25] neg_lo:[0,0,1] neg_hi:[0,0,1]
	v_pk_mul_f32 v[36:37], v[38:39], v[36:37]
	v_pk_mul_f32 v[40:41], v[40:41], v[132:133] op_sel_hi:[1,0]
	v_pk_mul_f32 v[28:29], v[28:29], v[82:83]
	v_pk_fma_f32 v[26:27], v[46:47], v[26:27], v[36:37]
	v_mov_b32_e32 v36, v20
	v_mov_b32_e32 v37, v22
	v_mov_b32_e32 v22, v21
	v_pk_mul_f32 v[40:41], v[40:41], v[88:89]
	v_pk_mul_f32 v[20:21], v[28:29], v[22:23]
	v_pk_mul_f32 v[28:29], v[28:29], v[36:37]
	v_pk_mul_f32 v[42:43], v[42:43], v[132:133] op_sel_hi:[1,0]
	v_pk_fma_f32 v[22:23], v[40:41], v[22:23], v[28:29]
	v_mov_b32_e32 v29, v18
	v_mov_b32_e32 v18, v17
	v_pk_mul_f32 v[42:43], v[42:43], v[84:85]
	v_mov_b32_e32 v28, v16
	v_pk_mul_f32 v[16:17], v[30:31], v[18:19]
	v_pk_fma_f32 v[60:61], v[80:81], v[76:77], v[60:61] neg_lo:[0,0,1] neg_hi:[0,0,1]
	v_pk_fma_f32 v[16:17], v[42:43], v[28:29], v[16:17] neg_lo:[0,0,1] neg_hi:[0,0,1]
	v_pk_mul_f32 v[28:29], v[30:31], v[28:29]
	v_pk_fma_f32 v[52:53], v[68:69], v[72:73], v[52:53] neg_lo:[0,0,1] neg_hi:[0,0,1]
	v_pk_fma_f32 v[32:33], v[44:45], v[64:65], v[32:33] neg_lo:[0,0,1] neg_hi:[0,0,1]
	v_pk_fma_f32 v[20:21], v[40:41], v[36:37], v[20:21] neg_lo:[0,0,1] neg_hi:[0,0,1]
	v_pk_fma_f32 v[18:19], v[42:43], v[18:19], v[28:29]
	v_cvt_pk_bf16_f32 v140, v60, v61
	v_cvt_pk_bf16_f32 v141, v56, v57
	v_cvt_pk_bf16_f32 v142, v52, v53
	v_cvt_pk_bf16_f32 v143, v48, v49
	v_cvt_pk_bf16_f32 v144, v62, v63
	v_cvt_pk_bf16_f32 v145, v58, v59
	v_cvt_pk_bf16_f32 v146, v54, v55
	v_cvt_pk_bf16_f32 v147, v50, v51
	v_cvt_pk_bf16_f32 v136, v32, v33
	v_cvt_pk_bf16_f32 v137, v24, v25
	v_cvt_pk_bf16_f32 v138, v20, v21
	v_cvt_pk_bf16_f32 v139, v16, v17
	v_cvt_pk_bf16_f32 v132, v34, v35
	v_cvt_pk_bf16_f32 v133, v26, v27
	v_cvt_pk_bf16_f32 v134, v22, v23
	v_cvt_pk_bf16_f32 v135, v18, v19
	v_mov_b32_e32 v64, 0
	v_mov_b32_e32 v65, 0
	v_mov_b32_e32 v66, 0
	v_mov_b32_e32 v67, 0
	v_mov_b32_e32 v68, 0
	v_mov_b32_e32 v69, 0
	v_mov_b32_e32 v70, 0
	v_mov_b32_e32 v71, 0
	v_mov_b32_e32 v72, 0
	v_mov_b32_e32 v73, 0
	v_mov_b32_e32 v74, 0
	v_mov_b32_e32 v75, 0
	v_mov_b32_e32 v76, 0
	v_mov_b32_e32 v77, 0
	v_mov_b32_e32 v78, 0
	v_mov_b32_e32 v79, 0
	v_mov_b32_e32 v48, 0
	v_mov_b32_e32 v49, 0
	v_mov_b32_e32 v50, 0
	v_mov_b32_e32 v51, 0
	v_mov_b32_e32 v52, 0
	v_mov_b32_e32 v53, 0
	v_mov_b32_e32 v54, 0
	v_mov_b32_e32 v55, 0
	v_mov_b32_e32 v56, 0
	v_mov_b32_e32 v57, 0
	v_mov_b32_e32 v58, 0
	v_mov_b32_e32 v59, 0
	v_mov_b32_e32 v60, 0
	v_mov_b32_e32 v61, 0
	v_mov_b32_e32 v62, 0
	v_mov_b32_e32 v63, 0
	v_mov_b32_e32 v32, 0
	v_mov_b32_e32 v33, 0
	v_mov_b32_e32 v34, 0
	v_mov_b32_e32 v35, 0
	v_mov_b32_e32 v36, 0
	v_mov_b32_e32 v37, 0
	v_mov_b32_e32 v38, 0
	v_mov_b32_e32 v39, 0
	v_mov_b32_e32 v40, 0
	v_mov_b32_e32 v41, 0
	v_mov_b32_e32 v42, 0
	v_mov_b32_e32 v43, 0
	v_mov_b32_e32 v44, 0
	v_mov_b32_e32 v45, 0
	v_mov_b32_e32 v46, 0
	v_mov_b32_e32 v47, 0
	v_mov_b32_e32 v16, 0
	v_mov_b32_e32 v17, 0
	v_mov_b32_e32 v18, 0
	v_mov_b32_e32 v19, 0
	v_mov_b32_e32 v20, 0
	v_mov_b32_e32 v21, 0
	v_mov_b32_e32 v22, 0
	v_mov_b32_e32 v23, 0
	v_mov_b32_e32 v24, 0
	v_mov_b32_e32 v25, 0
	v_mov_b32_e32 v26, 0
	v_mov_b32_e32 v27, 0
	v_mov_b32_e32 v28, 0
	v_mov_b32_e32 v29, 0
	v_mov_b32_e32 v30, 0
	v_mov_b32_e32 v31, 0
	v_mov_b32_e32 v80, 0xf149f2ca
	v_mov_b32_e32 v81, 0xf149f2ca
	v_mov_b32_e32 v82, 0xf149f2ca
	v_mov_b32_e32 v83, 0xf149f2ca
	v_mov_b32_e32 v84, 0xf149f2ca
	v_mov_b32_e32 v85, 0xf149f2ca
	v_mov_b32_e32 v86, 0xf149f2ca
	v_mov_b32_e32 v87, 0xf149f2ca
	v_mov_b32_e32 v88, 0xf149f2ca
	v_mov_b32_e32 v89, 0xf149f2ca
	v_mov_b32_e32 v90, 0xf149f2ca
	v_mov_b32_e32 v91, 0xf149f2ca
	v_mov_b32_e32 v92, 0xf149f2ca
	v_mov_b32_e32 v93, 0xf149f2ca
	v_mov_b32_e32 v94, 0xf149f2ca
	v_mov_b32_e32 v95, 0xf149f2ca
	v_mov_b32_e32 v225, 0
	v_mov_b32_e32 v166, 0
	v_mov_b32_e32 v175, 0
	v_mov_b32_e32 v202, 0
	s_waitcnt vmcnt(8)
	s_barrier
	ds_read_b128 v[112:115], v178
	ds_read_b128 v[116:119], v128
	ds_read_b128 v[120:123], v130
	ds_read_b128 v[124:127], v131
	s_mov_b32 s16, 0
	s_cmpk_ge_u32 s17, 0x2000
	s_cbranch_scc0 .Latt_prio_done
	s_setprio 1
.Latt_prio_done:
.Latt_loop:
	s_waitcnt lgkmcnt(3)
	v_mfma_f32_32x32x16_bf16 v[96:111], v[112:115], v[140:143], v[0:15]
	v_exp_f32_e32 v209, v80
	v_exp_f32_e32 v210, v81
	ds_read_b64_tr_b16 v[226:227], v198 offset:40960
	ds_read_b64_tr_b16 v[228:229], v198 offset:43008
	s_waitcnt lgkmcnt(4)
	v_mfma_f32_32x32x16_bf16 v[96:111], v[116:119], v[144:147], v[96:111]
	v_exp_f32_e32 v211, v82
	v_exp_f32_e32 v212, v83
	v_cvt_pk_bf16_f32 v156, v209, v210
	ds_read_b64_tr_b16 v[230:231], v199 offset:40960
	ds_read_b64_tr_b16 v[232:233], v199 offset:43008
	s_waitcnt lgkmcnt(5)
	v_mfma_f32_32x32x16_bf16 v[96:111], v[120:123], v[136:139], v[96:111]
	v_exp_f32_e32 v213, v84
	v_exp_f32_e32 v214, v85
	v_cvt_pk_bf16_f32 v157, v211, v212
	ds_read_b64_tr_b16 v[234:235], v201 offset:40960
	ds_read_b64_tr_b16 v[236:237], v201 offset:43008
	s_waitcnt lgkmcnt(6)
	v_mfma_f32_32x32x16_bf16 v[96:111], v[124:127], v[132:135], v[96:111]
	v_exp_f32_e32 v215, v86
	v_exp_f32_e32 v216, v87
	v_cvt_pk_bf16_f32 v158, v213, v214
	v_cvt_pk_bf16_f32 v159, v215, v216
	ds_read_b64_tr_b16 v[238:239], v203 offset:40960
	ds_read_b64_tr_b16 v[240:241], v203 offset:43008
	s_waitcnt lgkmcnt(6)
	v_mfma_f32_32x32x16_bf16 v[64:79], v[226:229], v[156:159], v[64:79]
	v_exp_f32_e32 v217, v88
	v_exp_f32_e32 v218, v89
	ds_read_b64_tr_b16 v[242:243], v198 offset:45056
	ds_read_b64_tr_b16 v[244:245], v198 offset:47104
	s_waitcnt lgkmcnt(6)
	v_mfma_f32_32x32x16_bf16 v[48:63], v[230:233], v[156:159], v[48:63]
	v_exp_f32_e32 v219, v90
	v_exp_f32_e32 v220, v91
	v_cvt_pk_bf16_f32 v160, v217, v218
	ds_read_b64_tr_b16 v[246:247], v199 offset:45056
	ds_read_b64_tr_b16 v[248:249], v199 offset:47104
	s_waitcnt lgkmcnt(6)
	v_mfma_f32_32x32x16_bf16 v[32:47], v[234:237], v[156:159], v[32:47]
	v_exp_f32_e32 v221, v92
	v_exp_f32_e32 v222, v93
	v_cvt_pk_bf16_f32 v161, v219, v220
	ds_read_b64_tr_b16 v[226:227], v201 offset:45056
	ds_read_b64_tr_b16 v[228:229], v201 offset:47104
	s_waitcnt lgkmcnt(6)
	v_mfma_f32_32x32x16_bf16 v[16:31], v[238:241], v[156:159], v[16:31]
	v_exp_f32_e32 v223, v94
	v_exp_f32_e32 v224, v95
	v_cvt_pk_bf16_f32 v162, v221, v222
	v_cvt_pk_bf16_f32 v163, v223, v224
	ds_read_b64_tr_b16 v[230:231], v203 offset:45056
	ds_read_b64_tr_b16 v[232:233], v203 offset:47104
	s_waitcnt lgkmcnt(6)
	v_mfma_f32_32x32x16_bf16 v[64:79], v[242:245], v[160:163], v[64:79]
	v_add_f32_e32 v225, v225, v209
	v_add_f32_e32 v166, v166, v210
	v_add_f32_e32 v175, v175, v211
	v_add_f32_e32 v202, v202, v212
	ds_read_b128 v[112:115], v178 offset:8192
	s_waitcnt lgkmcnt(5)
	v_mfma_f32_32x32x16_bf16 v[48:63], v[246:249], v[160:163], v[48:63]
	v_add_f32_e32 v225, v225, v213
	v_add_f32_e32 v166, v166, v214
	v_add_f32_e32 v175, v175, v215
	v_add_f32_e32 v202, v202, v216
	ds_read_b128 v[116:119], v128 offset:8192
	s_waitcnt lgkmcnt(4)
	v_mfma_f32_32x32x16_bf16 v[32:47], v[226:229], v[160:163], v[32:47]
	v_add_f32_e32 v225, v225, v217
	v_add_f32_e32 v166, v166, v218
	v_add_f32_e32 v175, v175, v219
	v_add_f32_e32 v202, v202, v220
	ds_read_b128 v[120:123], v130 offset:8192
	s_waitcnt lgkmcnt(3)
	v_mfma_f32_32x32x16_bf16 v[16:31], v[230:233], v[160:163], v[16:31]
	v_add_f32_e32 v225, v225, v221
	v_add_f32_e32 v166, v166, v222
	v_add_f32_e32 v175, v175, v223
	v_add_f32_e32 v202, v202, v224
	ds_read_b128 v[124:127], v131 offset:8192
	s_waitcnt lgkmcnt(3)
	v_mfma_f32_32x32x16_bf16 v[80:95], v[112:115], v[140:143], v[0:15]
	v_exp_f32_e32 v209, v96
	v_exp_f32_e32 v210, v97
	ds_read_b64_tr_b16 v[234:235], v184
	ds_read_b64_tr_b16 v[236:237], v184 offset:2048
	s_waitcnt lgkmcnt(4)
	v_mfma_f32_32x32x16_bf16 v[80:95], v[116:119], v[144:147], v[80:95]
	v_exp_f32_e32 v211, v98
	v_exp_f32_e32 v212, v99
	v_cvt_pk_bf16_f32 v148, v209, v210
	ds_read_b64_tr_b16 v[238:239], v185
	ds_read_b64_tr_b16 v[240:241], v185 offset:2048
	s_waitcnt lgkmcnt(5)
	v_mfma_f32_32x32x16_bf16 v[80:95], v[120:123], v[136:139], v[80:95]
	v_exp_f32_e32 v213, v100
	v_exp_f32_e32 v214, v101
	v_cvt_pk_bf16_f32 v149, v211, v212
	ds_read_b64_tr_b16 v[242:243], v186
	ds_read_b64_tr_b16 v[244:245], v186 offset:2048
	s_waitcnt lgkmcnt(6)
	v_mfma_f32_32x32x16_bf16 v[80:95], v[124:127], v[132:135], v[80:95]
	v_exp_f32_e32 v215, v102
	v_exp_f32_e32 v216, v103
	v_cvt_pk_bf16_f32 v150, v213, v214
	v_cvt_pk_bf16_f32 v151, v215, v216
	ds_read_b64_tr_b16 v[246:247], v187
	ds_read_b64_tr_b16 v[248:249], v187 offset:2048
	s_waitcnt lgkmcnt(6)
	v_mfma_f32_32x32x16_bf16 v[64:79], v[234:237], v[148:151], v[64:79]
	v_exp_f32_e32 v217, v104
	v_exp_f32_e32 v218, v105
	ds_read_b64_tr_b16 v[226:227], v184 offset:4096
	ds_read_b64_tr_b16 v[228:229], v184 offset:6144
	s_waitcnt lgkmcnt(6)
	v_mfma_f32_32x32x16_bf16 v[48:63], v[238:241], v[148:151], v[48:63]
	v_exp_f32_e32 v219, v106
	v_exp_f32_e32 v220, v107
	v_cvt_pk_bf16_f32 v152, v217, v218
	ds_read_b64_tr_b16 v[230:231], v185 offset:4096
	ds_read_b64_tr_b16 v[232:233], v185 offset:6144
	s_waitcnt lgkmcnt(6)
	v_mfma_f32_32x32x16_bf16 v[32:47], v[242:245], v[148:151], v[32:47]
	v_exp_f32_e32 v221, v108
	v_exp_f32_e32 v222, v109
	v_cvt_pk_bf16_f32 v153, v219, v220
	ds_read_b64_tr_b16 v[234:235], v186 offset:4096
	ds_read_b64_tr_b16 v[236:237], v186 offset:6144
	s_waitcnt lgkmcnt(6)
	v_mfma_f32_32x32x16_bf16 v[16:31], v[246:249], v[148:151], v[16:31]
	v_exp_f32_e32 v223, v110
	v_exp_f32_e32 v224, v111
	v_cvt_pk_bf16_f32 v154, v221, v222
	v_cvt_pk_bf16_f32 v155, v223, v224
	ds_read_b64_tr_b16 v[238:239], v187 offset:4096
	ds_read_b64_tr_b16 v[240:241], v187 offset:6144
	s_waitcnt lgkmcnt(6)
	v_mfma_f32_32x32x16_bf16 v[64:79], v[226:229], v[152:155], v[64:79]
	s_waitcnt vmcnt(4)
	s_barrier
	s_and_b32 s1, s35, 3
	s_add_i32 s35, s35, 1
	s_cmp_lg_u32 s1, 0
	s_cbranch_scc1 .Latt_bs_0
	v_lshlrev_b32_e32 v204, 16, v194
	v_and_b32_e32 v205, 0xffff0000, v194
	v_fma_f32 v182, v174, v182, v204
	v_fma_f32 v183, v174, v183, v205
	s_lshr_b32 s1, s35, 2
	s_add_i32 s1, s1, 1
	s_cmpk_lt_u32 s1, 0x84
	s_cbranch_scc0 .Latt_bs_0
	s_lshl_b32 s2, s1, 14
	s_mov_b32 s3, 0
	s_lshl_b32 s4, s1, 8
	s_mov_b32 s5, 0
	v_lshl_add_u64 v[204:205], v[168:169], 0, s[2:3]
	v_lshl_add_u64 v[196:197], v[170:171], 0, s[4:5]
	v_cvt_pk_bf16_f32 v206, v182, v183
	global_load_dword v194, v[204:205], off
	global_load_dword v174, v[196:197], off
	global_store_dword v[204:205], v206, off

.Latt_bs_3:
	v_add_f32_e32 v225, v225, v209
	v_add_f32_e32 v166, v166, v210
	v_add_f32_e32 v175, v175, v211
	v_add_f32_e32 v202, v202, v212
	s_add_i32 m0, s17, 65536
	ds_read_b128 v[112:115], v178
	global_load_lds_dwordx4 v181, s[36:37]
	s_waitcnt lgkmcnt(5)
	v_mfma_f32_32x32x16_bf16 v[48:63], v[230:233], v[152:155], v[48:63]
	v_add_f32_e32 v225, v225, v213
	v_add_f32_e32 v166, v166, v214
	v_add_f32_e32 v175, v175, v215
	v_add_f32_e32 v202, v202, v216
	s_add_i32 m0, s17, 66560
	ds_read_b128 v[116:119], v128
	global_load_lds_dwordx4 v165, s[36:37]
	s_waitcnt lgkmcnt(4)
	v_mfma_f32_32x32x16_bf16 v[32:47], v[234:237], v[152:155], v[32:47]
	v_add_f32_e32 v225, v225, v217
	v_add_f32_e32 v166, v166, v218
	v_add_f32_e32 v175, v175, v219
	v_add_f32_e32 v202, v202, v220
	s_add_i32 m0, s17, 81920
	ds_read_b128 v[120:123], v130
	global_load_lds_dwordx4 v207, s[36:37]
	s_waitcnt lgkmcnt(3)
	v_mfma_f32_32x32x16_bf16 v[16:31], v[238:241], v[152:155], v[16:31]
	v_add_f32_e32 v225, v225, v221
	v_add_f32_e32 v166, v166, v222
	v_add_f32_e32 v175, v175, v223
	v_add_f32_e32 v202, v202, v224
	s_add_i32 m0, s17, 82944
	ds_read_b128 v[124:127], v131
	global_load_lds_dwordx4 v208, s[36:37]
	s_add_u32 s36, s36, 0x68000
	s_addc_u32 s37, s37, 0
	s_cmp_eq_u32 s16, 0
	s_cselect_b32 s36, s38, s36
	s_cselect_b32 s37, s39, s37
	s_add_i32 s16, s16, 1
	s_cmpk_lt_u32 s16, 0x84
	s_cbranch_scc1 .Latt_loop
	s_setprio 0
	ds_read_b64_tr_b16 v[226:227], v198 offset:40960
	ds_read_b64_tr_b16 v[228:229], v198 offset:43008
	ds_read_b64_tr_b16 v[230:231], v199 offset:40960
	ds_read_b64_tr_b16 v[232:233], v199 offset:43008
	ds_read_b64_tr_b16 v[234:235], v201 offset:40960
	ds_read_b64_tr_b16 v[236:237], v201 offset:43008
	ds_read_b64_tr_b16 v[238:239], v203 offset:40960
	ds_read_b64_tr_b16 v[240:241], v203 offset:43008
	ds_read_b64_tr_b16 v[242:243], v198 offset:45056
	ds_read_b64_tr_b16 v[244:245], v198 offset:47104
	ds_read_b64_tr_b16 v[246:247], v199 offset:45056
	ds_read_b64_tr_b16 v[248:249], v199 offset:47104
	ds_read_b64_tr_b16 v[112:113], v201 offset:45056
	ds_read_b64_tr_b16 v[114:115], v201 offset:47104
	ds_read_b64_tr_b16 v[120:121], v203 offset:45056
	ds_read_b64_tr_b16 v[122:123], v203 offset:47104
	v_exp_f32_e32 v209, v80
	v_exp_f32_e32 v210, v81
	v_exp_f32_e32 v211, v82
	v_exp_f32_e32 v212, v83
	v_exp_f32_e32 v213, v84
	v_exp_f32_e32 v214, v85
	v_exp_f32_e32 v215, v86
	v_exp_f32_e32 v216, v87
	v_exp_f32_e32 v217, v88
	v_exp_f32_e32 v218, v89
	v_exp_f32_e32 v219, v90
	v_exp_f32_e32 v220, v91
	v_exp_f32_e32 v221, v92
	v_exp_f32_e32 v222, v93
	v_exp_f32_e32 v223, v94
	v_exp_f32_e32 v224, v95
	s_nop 0
	v_cvt_pk_bf16_f32 v156, v209, v210
	v_cvt_pk_bf16_f32 v157, v211, v212
	v_cvt_pk_bf16_f32 v158, v213, v214
	v_cvt_pk_bf16_f32 v159, v215, v216
	v_cvt_pk_bf16_f32 v160, v217, v218
	v_cvt_pk_bf16_f32 v161, v219, v220
	v_cvt_pk_bf16_f32 v162, v221, v222
	v_cvt_pk_bf16_f32 v163, v223, v224
	v_add_f32_e32 v225, v225, v209
	v_add_f32_e32 v166, v166, v210
	v_add_f32_e32 v175, v175, v211
	v_add_f32_e32 v202, v202, v212
	v_add_f32_e32 v225, v225, v213
	v_add_f32_e32 v166, v166, v214
	v_add_f32_e32 v175, v175, v215
	v_add_f32_e32 v202, v202, v216
	v_add_f32_e32 v225, v225, v217
	v_add_f32_e32 v166, v166, v218
	v_add_f32_e32 v175, v175, v219
	v_add_f32_e32 v202, v202, v220
	v_add_f32_e32 v225, v225, v221
	v_add_f32_e32 v166, v166, v222
	v_add_f32_e32 v175, v175, v223
	v_add_f32_e32 v202, v202, v224
	s_waitcnt lgkmcnt(0)
	v_mfma_f32_32x32x16_bf16 v[64:79], v[226:229], v[156:159], v[64:79]
	v_mfma_f32_32x32x16_bf16 v[48:63], v[230:233], v[156:159], v[48:63]
	v_mfma_f32_32x32x16_bf16 v[32:47], v[234:237], v[156:159], v[32:47]
	v_mfma_f32_32x32x16_bf16 v[16:31], v[238:241], v[156:159], v[16:31]
	v_mfma_f32_32x32x16_bf16 v[64:79], v[242:245], v[160:163], v[64:79]
	v_mfma_f32_32x32x16_bf16 v[48:63], v[246:249], v[160:163], v[48:63]
	v_mfma_f32_32x32x16_bf16 v[32:47], v[112:115], v[160:163], v[32:47]
	v_mfma_f32_32x32x16_bf16 v[16:31], v[120:123], v[160:163], v[16:31]
	v_add_f32_e32 v225, v225, v166
	v_add_f32_e32 v175, v175, v202
	v_add_f32_e32 v80, v225, v175
	v_and_b32_e32 v196, 63, v188
	s_cmpk_lt_u32 s34, 0x100
	s_cselect_b64 s[4:5], -1, 0
	s_lshl_b32 s0, s31, 14
	s_waitcnt vmcnt(0)
	s_barrier
	ds_bpermute_b32 v81, v195, v80
	s_nop 7
	s_nop 7
	s_cmp_eq_u32 s30, 1
	s_waitcnt lgkmcnt(0)
	v_add_f32_e32 v80, v80, v81
	v_cndmask_b32_e64 v81, v164, 1.0, s[4:5]
	v_div_scale_f32 v82, s[16:17], v80, v80, v81
	v_rcp_f32_e32 v83, v82
	s_nop 0
	v_fma_f32 v84, -v82, v83, 1.0
	v_fmac_f32_e32 v83, v84, v83
	v_div_scale_f32 v84, vcc, v81, v80, v81
	v_mul_f32_e32 v85, v84, v83
	v_fma_f32 v86, -v82, v85, v84
	v_fmac_f32_e32 v85, v86, v83
	v_fma_f32 v82, -v82, v85, v84
	v_div_fmas_f32 v82, v82, v83, v85
	v_div_fixup_f32 v92, v82, v80, v81
	v_pk_mul_f32 v[88:89], v[64:65], v[92:93] op_sel_hi:[1,0]
	v_pk_mul_f32 v[90:91], v[66:67], v[92:93] op_sel_hi:[1,0]
	v_pk_mul_f32 v[82:83], v[68:69], v[92:93] op_sel_hi:[1,0]
	v_pk_mul_f32 v[86:87], v[70:71], v[92:93] op_sel_hi:[1,0]
	v_pk_mul_f32 v[80:81], v[72:73], v[92:93] op_sel_hi:[1,0]
	v_pk_mul_f32 v[84:85], v[74:75], v[92:93] op_sel_hi:[1,0]
	v_pk_mul_f32 v[72:73], v[76:77], v[92:93] op_sel_hi:[1,0]
	v_pk_mul_f32 v[78:79], v[78:79], v[92:93] op_sel_hi:[1,0]
	v_pk_mul_f32 v[68:69], v[48:49], v[92:93] op_sel_hi:[1,0]
	v_pk_mul_f32 v[76:77], v[50:51], v[92:93] op_sel_hi:[1,0]
	v_pk_mul_f32 v[66:67], v[52:53], v[92:93] op_sel_hi:[1,0]
	v_pk_mul_f32 v[74:75], v[54:55], v[92:93] op_sel_hi:[1,0]
	v_pk_mul_f32 v[64:65], v[56:57], v[92:93] op_sel_hi:[1,0]
	v_pk_mul_f32 v[70:71], v[58:59], v[92:93] op_sel_hi:[1,0]
	v_pk_mul_f32 v[54:55], v[60:61], v[92:93] op_sel_hi:[1,0]
	v_pk_mul_f32 v[60:61], v[62:63], v[92:93] op_sel_hi:[1,0]
	v_pk_mul_f32 v[50:51], v[32:33], v[92:93] op_sel_hi:[1,0]
	v_pk_mul_f32 v[58:59], v[34:35], v[92:93] op_sel_hi:[1,0]
	v_pk_mul_f32 v[48:49], v[36:37], v[92:93] op_sel_hi:[1,0]
	v_pk_mul_f32 v[56:57], v[38:39], v[92:93] op_sel_hi:[1,0]
	v_pk_mul_f32 v[40:41], v[40:41], v[92:93] op_sel_hi:[1,0]
	v_pk_mul_f32 v[52:53], v[42:43], v[92:93] op_sel_hi:[1,0]
	v_pk_mul_f32 v[36:37], v[44:45], v[92:93] op_sel_hi:[1,0]
	v_pk_mul_f32 v[44:45], v[46:47], v[92:93] op_sel_hi:[1,0]
	v_pk_mul_f32 v[34:35], v[16:17], v[92:93] op_sel_hi:[1,0]
	v_pk_mul_f32 v[42:43], v[18:19], v[92:93] op_sel_hi:[1,0]
	v_pk_mul_f32 v[32:33], v[20:21], v[92:93] op_sel_hi:[1,0]
	v_pk_mul_f32 v[38:39], v[22:23], v[92:93] op_sel_hi:[1,0]
	v_pk_mul_f32 v[20:21], v[24:25], v[92:93] op_sel_hi:[1,0]
	v_pk_mul_f32 v[22:23], v[26:27], v[92:93] op_sel_hi:[1,0]
	v_pk_mul_f32 v[16:17], v[28:29], v[92:93] op_sel_hi:[1,0]
	v_pk_mul_f32 v[18:19], v[30:31], v[92:93] op_sel_hi:[1,0]
	v_lshl_add_u32 v24, v196, 2, s0
	s_cbranch_scc0 .LBB0_446
	ds_write2st64_b32 v24, v88, v89 offset1:1
	ds_write2st64_b32 v24, v90, v91 offset0:2 offset1:3
	ds_write2st64_b32 v24, v82, v83 offset0:4 offset1:5
	ds_write2st64_b32 v24, v86, v87 offset0:6 offset1:7
	ds_write2st64_b32 v24, v80, v81 offset0:8 offset1:9
	ds_write2st64_b32 v24, v84, v85 offset0:10 offset1:11
	ds_write2st64_b32 v24, v72, v73 offset0:12 offset1:13
	ds_write2st64_b32 v24, v78, v79 offset0:14 offset1:15
	ds_write2st64_b32 v24, v68, v69 offset0:16 offset1:17
	ds_write2st64_b32 v24, v76, v77 offset0:18 offset1:19
	ds_write2st64_b32 v24, v66, v67 offset0:20 offset1:21
	ds_write2st64_b32 v24, v74, v75 offset0:22 offset1:23
	ds_write2st64_b32 v24, v64, v65 offset0:24 offset1:25
	ds_write2st64_b32 v24, v70, v71 offset0:26 offset1:27
	ds_write2st64_b32 v24, v54, v55 offset0:28 offset1:29
	ds_write2st64_b32 v24, v60, v61 offset0:30 offset1:31
	ds_write2st64_b32 v24, v50, v51 offset0:32 offset1:33
	ds_write2st64_b32 v24, v58, v59 offset0:34 offset1:35
	ds_write2st64_b32 v24, v48, v49 offset0:36 offset1:37
	ds_write2st64_b32 v24, v56, v57 offset0:38 offset1:39
	ds_write2st64_b32 v24, v40, v41 offset0:40 offset1:41
	ds_write2st64_b32 v24, v52, v53 offset0:42 offset1:43
	ds_write2st64_b32 v24, v36, v37 offset0:44 offset1:45
	ds_write2st64_b32 v24, v44, v45 offset0:46 offset1:47
	ds_write2st64_b32 v24, v34, v35 offset0:48 offset1:49
	ds_write2st64_b32 v24, v42, v43 offset0:50 offset1:51
	ds_write2st64_b32 v24, v32, v33 offset0:52 offset1:53
	ds_write2st64_b32 v24, v38, v39 offset0:54 offset1:55
	ds_write2st64_b32 v24, v20, v21 offset0:56 offset1:57
	ds_write2st64_b32 v24, v22, v23 offset0:58 offset1:59
	ds_write2st64_b32 v24, v16, v17 offset0:60 offset1:61
	ds_write2st64_b32 v24, v18, v19 offset0:62 offset1:63
